# indexer loops: sortable-key vcc form -> ashr/or/xor (15 sites) and mask copies through a VGPR -> s_mov_b64 (14 sites), both exact
# baseline (speedup 1.0000x reference)
; #define MFMA16(a, b, c) __builtin_amdgcn_mfma_f32_16x16x32_f16((a), (b), (c), 0, 0, 0)
; DI unsigned sortable(float f) { const unsigned u = __float_as_uint(f); return (u & 0x80000000u) ? ~u : (u | 0x80000000u); }
; template <int MODE> ...
;     ...
;   for (int n = wid; n < ntile; n += 4) {
;     {
;       const int nn = n + 4 < ntile ? n + 4 : n;
; #pragma unroll
;       for (int kt = 0; kt < 4; ++kt)
; #pragma unroll
;         for (int ks = 0; ks < 2; ++ks) kn[kt][ks] = *(const bf16x8*)(kbase + (size_t)(nn * 64 + kt * 16) * PW + ks * 32);
;     }
;     unsigned base[4] = {0u, 0u, 0u, 0u};
;     u64 word[4] = {0ull, 0ull, 0ull, 0ull};
;     u64 zword[4] = {0ull, 0ull, 0ull, 0ull};
;     if (MODE == 2 && any_tie) {
; #pragma unroll
;       for (int j = 0; j < 4; ++j) base[j] = cnt[(4 * g + j) * 64 + n];
;     }
; #pragma unroll
;     for (int kt = 0; kt < 4; ++kt) {
;       f32x4 sh[4];
; #pragma unroll
;       for (int h = 0; h < 4; ++h) {
;         sh[h] = (f32x4){0.f, 0.f, 0.f, 0.f};
; #pragma unroll
;         for (int ks = 0; ks < 2; ++ks) sh[h] = MFMA16(qf[h][ks], kf[kt][ks], sh[h]);
;       }
; #pragma unroll
;       for (int j = 0; j < 4; ++j) {
;         float sc = w[j][0] * fmaxf(sh[0][j], 0.f) + w[j][1] * fmaxf(sh[1][j], 0.f) + w[j][2] * fmaxf(sh[2][j], 0.f) + w[j][3] * fmaxf(sh[3][j], 0.f);
;         sc += 0.0f;
;         const unsigned u = sortable(sc);
;         if (MODE == 4) {
;           const unsigned um = u & himask;
;           const bool eq = um == pfx[j], zr = u == 0x80000000u;
;           unsigned* qx = hist + (4 * g + j) * C1_HP + 512;
;           if (eq) {
;             const unsigned bin = u & bmask; atomicAdd(&hist[(4 * g + j) * C1_HP + (bin >> 1)], 1u << ((bin & 1u) * 16u));
;             if (!zr) { const unsigned idx = atomicAdd(&qx[320], 1u); if (idx < 64u) qx[256 + idx] = ((unsigned)n << 16) | ((unsigned)(kt * 16 + lr) << 10) | (u & 1023u); }
;           }
;           word[j] |= (u64)((unsigned)(__ballot(um > pfx[j]) >> (16 * g)) & 0xffffu) << (16 * kt);
;           zword[j] |= (u64)((unsigned)(__ballot(zr) >> (16 * g)) & 0xffffu) << (16 * kt);
.LBB0_870:
	s_waitcnt vmcnt(6)
	v_mov_b64_e32 v[102:103], v[38:39]
	v_mov_b64_e32 v[58:59], v[34:35]
	v_mov_b64_e32 v[100:101], v[36:37]
	v_mov_b64_e32 v[56:57], v[32:33]
	v_mov_b32_e32 v36, v154
	v_add_u32_e32 v154, 4, v36
	v_mfma_f32_16x16x32_f16 v[60:63], v[12:15], v[56:59], 0
	v_cmp_lt_i32_e64 s[4:5], s2, v154
	v_mfma_f32_16x16x32_f16 v[32:35], v[24:27], v[56:59], 0
	s_nop 0
	v_cndmask_b32_e64 v36, v154, v36, s[4:5]
	v_lshlrev_b32_e32 v155, 6, v36
	v_or_b32_e32 v44, 16, v155
	v_mfma_f32_16x16x32_f16 v[40:43], v[4:7], v[56:59], 0
	v_or_b32_e32 v48, 32, v155
	v_mad_i64_i32 v[36:37], s[6:7], v155, s0, v[122:123]
	v_mfma_f32_16x16x32_f16 v[96:99], v[16:19], v[100:103], v[60:63]
	v_mad_i64_i32 v[44:45], s[6:7], v44, s0, v[122:123]
	v_mad_i64_i32 v[52:53], s[6:7], v48, s0, v[122:123]
	s_nop 0
	v_or_b32_e32 v60, 48, v155
	v_mad_i64_i32 v[60:61], s[6:7], v60, s0, v[122:123]
	v_mfma_f32_16x16x32_f16 v[88:91], v[0:3], v[100:103], v[32:35]
	s_nop 2
	global_load_dwordx4 v[32:35], v[36:37], off
	s_nop 0
	global_load_dwordx4 v[36:39], v[36:37], off offset:64
	s_nop 1
	v_mfma_f32_16x16x32_f16 v[92:95], v[8:11], v[100:103], v[40:43]
	s_nop 2
	global_load_dwordx4 v[40:43], v[44:45], off
	s_nop 0
	global_load_dwordx4 v[44:47], v[44:45], off offset:64
	s_nop 0
	global_load_dwordx4 v[48:51], v[52:53], off
	s_nop 0
	global_load_dwordx4 v[52:55], v[52:53], off offset:64
	v_mfma_f32_16x16x32_f16 v[156:159], v[20:23], v[56:59], 0
	global_load_dwordx4 v[56:59], v[60:61], off
	s_nop 0
	global_load_dwordx4 v[60:63], v[60:61], off offset:64
	v_mfma_f32_16x16x32_f16 v[100:103], v[28:31], v[100:103], v[156:159]
	s_nop 3
	v_max_f32_e32 v156, 0, v88
	v_max_f32_e32 v157, 0, v92
	v_max_f32_e32 v158, 0, v96
	v_pk_mul_f32 v[156:157], v[156:157], v[106:107]
	v_max_f32_e32 v159, 0, v100
	v_pk_mul_f32 v[158:159], v[158:159], v[108:109]
	v_add_f32_e32 v88, v156, v157
	v_add_f32_e32 v88, v88, v158
	v_add_f32_e32 v88, v88, v159
	v_add_f32_e32 v88, 0, v88
	v_ashrrev_i32_e32 v96, 31, v88
	v_or_b32_e32 v96, 0x80000000, v96
	v_xor_b32_e32 v92, v96, v88
	v_and_b32_e32 v88, s30, v92
	v_cmp_eq_u32_e64 s[8:9], v88, v142
	v_cmp_eq_u32_e32 vcc, s3, v92
	v_cmp_ne_u32_e64 s[6:7], s3, v92
	s_and_saveexec_b64 s[10:11], s[8:9]
	s_cbranch_execz .LBB0_874
	v_and_b32_e32 v96, s31, v92
	v_lshlrev_b32_e32 v100, 1, v96
	v_and_b32_e32 v100, -4, v100
	v_lshlrev_b32_e32 v96, 4, v96
	v_add_u32_e32 v100, v137, v100
	v_lshlrev_b32_e64 v96, v96, 1
	ds_add_u32 v100, v96
	s_and_b64 exec, exec, s[6:7]
	s_cbranch_execz .LBB0_874
	ds_add_rtn_u32 v96, v137, v174 offset:3328
	s_waitcnt lgkmcnt(0)
	v_cmp_gt_u32_e64 s[6:7], 64, v96
	s_and_b64 exec, exec, s[6:7]
	v_and_b32_e32 v92, 0x3ff, v92
	v_add_u32_e32 v92, v146, v92
	v_lshl_add_u32 v96, v96, 2, v137
	ds_write_b32 v96, v92 offset:3072
.LBB0_874:
	s_or_b64 exec, exec, s[10:11]
	v_cmp_gt_u32_e64 s[56:57], v88, v142
	s_mov_b64 s[58:59], vcc
	v_max_f32_e32 v88, 0, v89
	v_max_f32_e32 v89, 0, v93
	v_pk_mul_f32 v[88:89], v[88:89], v[110:111]
	v_max_f32_e32 v92, 0, v97
	v_max_f32_e32 v93, 0, v101
	v_pk_mul_f32 v[92:93], v[92:93], v[112:113]
	v_add_f32_e32 v88, v88, v89
	v_add_f32_e32 v88, v88, v92
	v_add_f32_e32 v88, v88, v93
	v_add_f32_e32 v88, 0, v88
	v_ashrrev_i32_e32 v92, 31, v88
	v_or_b32_e32 v92, 0x80000000, v92
	v_xor_b32_e32 v89, v92, v88
	v_and_b32_e32 v88, s30, v89
	v_cmp_eq_u32_e64 s[8:9], v88, v143
	v_cmp_eq_u32_e32 vcc, s3, v89
	v_cmp_ne_u32_e64 s[6:7], s3, v89
	s_and_saveexec_b64 s[10:11], s[8:9]
	s_cbranch_execz .LBB0_878
	v_and_b32_e32 v92, s31, v89
	v_lshlrev_b32_e32 v93, 1, v92
	v_and_b32_e32 v93, -4, v93
	v_lshlrev_b32_e32 v92, 4, v92
	v_add_u32_e32 v93, v137, v93
	v_lshlrev_b32_e64 v92, v92, 1
	ds_add_u32 v93, v92 offset:4112
	s_and_b64 exec, exec, s[6:7]
	s_cbranch_execz .LBB0_878
	ds_add_rtn_u32 v92, v137, v174 offset:7440
	s_waitcnt lgkmcnt(0)
	v_cmp_gt_u32_e64 s[6:7], 64, v92
	s_and_b64 exec, exec, s[6:7]
	v_and_b32_e32 v89, 0x3ff, v89
	v_add_u32_e32 v89, v146, v89
	v_lshl_add_u32 v92, v92, 2, v137
	ds_write_b32 v92, v89 offset:7184
.LBB0_878:
	s_or_b64 exec, exec, s[10:11]
	v_cmp_gt_u32_e64 s[60:61], v88, v143
	s_mov_b64 s[62:63], vcc
	v_max_f32_e32 v88, 0, v90
	v_max_f32_e32 v89, 0, v94
	v_max_f32_e32 v92, 0, v98
	v_pk_mul_f32 v[88:89], v[88:89], v[114:115]
	v_max_f32_e32 v93, 0, v102
	v_pk_mul_f32 v[92:93], v[92:93], v[116:117]
	v_add_f32_e32 v88, v88, v89
	v_add_f32_e32 v88, v88, v92
	v_add_f32_e32 v88, v88, v93
	v_add_f32_e32 v88, 0, v88
	v_ashrrev_i32_e32 v90, 31, v88
	v_or_b32_e32 v90, 0x80000000, v90
	v_xor_b32_e32 v89, v90, v88
	v_and_b32_e32 v88, s30, v89
	v_cmp_eq_u32_e64 s[8:9], v88, v144
	v_cmp_eq_u32_e32 vcc, s3, v89
	v_cmp_ne_u32_e64 s[6:7], s3, v89
	s_and_saveexec_b64 s[10:11], s[8:9]
	s_cbranch_execz .LBB0_882
	v_and_b32_e32 v90, s31, v89
	v_lshlrev_b32_e32 v92, 1, v90
	v_and_b32_e32 v92, -4, v92
	v_lshlrev_b32_e32 v90, 4, v90
	v_add_u32_e32 v92, v137, v92
	v_lshlrev_b32_e64 v90, v90, 1
	ds_add_u32 v92, v90 offset:8224
	s_and_b64 exec, exec, s[6:7]
	s_cbranch_execz .LBB0_882
	ds_add_rtn_u32 v90, v137, v174 offset:11552
	s_waitcnt lgkmcnt(0)
	v_cmp_gt_u32_e64 s[6:7], 64, v90
	s_and_b64 exec, exec, s[6:7]
	v_and_b32_e32 v89, 0x3ff, v89
	v_add_u32_e32 v89, v146, v89
	v_lshl_add_u32 v90, v90, 2, v137
	ds_write_b32 v90, v89 offset:11296
; #define MFMA16(a, b, c) __builtin_amdgcn_mfma_f32_16x16x32_f16((a), (b), (c), 0, 0, 0)
; template <int MODE> ...
;     ...
;     for (int kt = 0; kt < 4; ++kt) {
;       f32x4 sh[4];
; #pragma unroll
;       for (int h = 0; h < 4; ++h) {
;         sh[h] = (f32x4){0.f, 0.f, 0.f, 0.f};
; #pragma unroll
;         for (int ks = 0; ks < 2; ++ks) sh[h] = MFMA16(qf[h][ks], kf[kt][ks], sh[h]);
;       }
; #pragma unroll
;       for (int j = 0; j < 4; ++j) {
;         float sc = w[j][0] * fmaxf(sh[0][j], 0.f) + w[j][1] * fmaxf(sh[1][j], 0.f) + w[j][2] * fmaxf(sh[2][j], 0.f) + w[j][3] * fmaxf(sh[3][j], 0.f);
;         sc += 0.0f;
;         const unsigned u = sortable(sc);
;         if (MODE == 4) {
;           const unsigned um = u & himask;
;           const bool eq = um == pfx[j], zr = u == 0x80000000u;
;           unsigned* qx = hist + (4 * g + j) * C1_HP + 512;
;           if (eq) {
;             const unsigned bin = u & bmask; atomicAdd(&hist[(4 * g + j) * C1_HP + (bin >> 1)], 1u << ((bin & 1u) * 16u));
;             if (!zr) { const unsigned idx = atomicAdd(&qx[320], 1u); if (idx < 64u) qx[256 + idx] = ((unsigned)n << 16) | ((unsigned)(kt * 16 + lr) << 10) | (u & 1023u); }
;           }
;           word[j] |= (u64)((unsigned)(__ballot(um > pfx[j]) >> (16 * g)) & 0xffffu) << (16 * kt);
;           zword[j] |= (u64)((unsigned)(__ballot(zr) >> (16 * g)) & 0xffffu) << (16 * kt);
;         } else if (MODE == 0 || MODE == 3) {
;           if (MODE == 3) base[j] += __popc((unsigned)(__ballot(u == 0x80000000u) >> (16 * g)) & 0xffffu);
;           if (((u ^ pfx[j]) & himask) == 0u) { const unsigned bin = (u >> shift) & bmask; atomicAdd(&hist[(4 * g + j) * C1_HP + (bin >> 1)], 1u << ((bin & 1u) * 16u)); }
;         } else {
;           const bool eq = u == pfx[j];
;           const unsigned fe = (unsigned)(__ballot(eq) >> (16 * g)) & 0xffffu;
;           if (MODE == 1) {
;             base[j] += __popc(fe);
;           } else {
;             const unsigned rank = base[j] + __popc(fe & ((1u << lr) - 1u));
;             const bool sel = (u > pfx[j]) || (eq && rank < need[j]);
;             base[j] += __popc(fe);
;             const unsigned fs = (unsigned)(__ballot(sel) >> (16 * g)) & 0xffffu;
;             word[j] |= (u64)fs << (16 * kt);
;           }
;         }
;       }
.LBB0_882:
	s_or_b64 exec, exec, s[10:11]
	v_cmp_gt_u32_e64 s[68:69], v88, v144
	s_mov_b64 s[70:71], vcc
	v_max_f32_e32 v88, 0, v91
	v_max_f32_e32 v89, 0, v95
	v_pk_mul_f32 v[88:89], v[88:89], v[118:119]
	v_max_f32_e32 v90, 0, v99
	v_max_f32_e32 v91, 0, v103
	v_pk_mul_f32 v[90:91], v[90:91], v[120:121]
	v_add_f32_e32 v88, v88, v89
	v_add_f32_e32 v88, v88, v90
	v_add_f32_e32 v88, v88, v91
	v_add_f32_e32 v88, 0, v88
	v_ashrrev_i32_e32 v90, 31, v88
	v_or_b32_e32 v90, 0x80000000, v90
	v_xor_b32_e32 v89, v90, v88
	v_and_b32_e32 v88, s30, v89
	v_cmp_eq_u32_e64 s[8:9], v88, v145
	v_cmp_eq_u32_e32 vcc, s3, v89
	v_cmp_ne_u32_e64 s[6:7], s3, v89
	s_and_saveexec_b64 s[10:11], s[8:9]
	s_cbranch_execz .LBB0_886
	v_and_b32_e32 v90, s31, v89
	v_lshlrev_b32_e32 v91, 1, v90
	v_and_b32_e32 v91, -4, v91
	v_lshlrev_b32_e32 v90, 4, v90
	v_add_u32_e32 v91, v137, v91
	v_lshlrev_b32_e64 v90, v90, 1
	ds_add_u32 v91, v90 offset:12336
	s_and_b64 exec, exec, s[6:7]
	s_cbranch_execz .LBB0_886
	ds_add_rtn_u32 v90, v137, v174 offset:15664
	s_waitcnt lgkmcnt(0)
	v_cmp_gt_u32_e64 s[6:7], 64, v90
	s_and_b64 exec, exec, s[6:7]
	v_and_b32_e32 v89, 0x3ff, v89
	v_add_u32_e32 v89, v146, v89
	v_lshl_add_u32 v90, v90, 2, v137
	ds_write_b32 v90, v89 offset:15408
.LBB0_886:
	s_or_b64 exec, exec, s[10:11]
	v_cmp_gt_u32_e64 s[64:65], v88, v145
	s_mov_b64 s[66:67], vcc
	s_waitcnt vmcnt(13)
	v_mfma_f32_16x16x32_f16 v[88:91], v[24:27], v[80:83], 0
	v_mfma_f32_16x16x32_f16 v[92:95], v[4:7], v[80:83], 0
	v_mfma_f32_16x16x32_f16 v[96:99], v[12:15], v[80:83], 0
	v_mfma_f32_16x16x32_f16 v[80:83], v[20:23], v[80:83], 0
	s_waitcnt vmcnt(12)
	v_mfma_f32_16x16x32_f16 v[88:91], v[0:3], v[84:87], v[88:91]
	v_mfma_f32_16x16x32_f16 v[92:95], v[8:11], v[84:87], v[92:95]
	v_mfma_f32_16x16x32_f16 v[96:99], v[16:19], v[84:87], v[96:99]
	v_mfma_f32_16x16x32_f16 v[80:83], v[28:31], v[84:87], v[80:83]
	s_nop 4
	v_max_f32_e32 v84, 0, v88
	v_max_f32_e32 v85, 0, v92
	v_pk_mul_f32 v[84:85], v[84:85], v[106:107]
	v_max_f32_e32 v86, 0, v96
	v_max_f32_e32 v87, 0, v80
	v_pk_mul_f32 v[86:87], v[86:87], v[108:109]
	v_add_f32_e32 v80, v84, v85
	v_add_f32_e32 v80, v80, v86
	v_add_f32_e32 v80, v80, v87
	v_add_f32_e32 v80, 0, v80
	v_ashrrev_i32_e32 v85, 31, v80
	v_or_b32_e32 v85, 0x80000000, v85
	v_xor_b32_e32 v84, v85, v80
	v_and_b32_e32 v80, s30, v84
	v_cmp_eq_u32_e64 s[8:9], v80, v142
	v_cmp_eq_u32_e32 vcc, s3, v84
	v_cmp_ne_u32_e64 s[6:7], s3, v84
	s_and_saveexec_b64 s[10:11], s[8:9]
	s_cbranch_execz .LBB0_890
	v_and_b32_e32 v85, s31, v84
	v_lshlrev_b32_e32 v86, 1, v85
	v_and_b32_e32 v86, -4, v86
	v_lshlrev_b32_e32 v85, 4, v85
	v_add_u32_e32 v86, v137, v86
	v_lshlrev_b32_e64 v85, v85, 1
	ds_add_u32 v86, v85
	s_and_b64 exec, exec, s[6:7]
	s_cbranch_execz .LBB0_890
	ds_add_rtn_u32 v85, v137, v174 offset:3328
	s_waitcnt lgkmcnt(0)
	v_cmp_gt_u32_e64 s[6:7], 64, v85
	s_and_b64 exec, exec, s[6:7]
	v_and_b32_e32 v84, 0x3ff, v84
	s_movk_i32 s6, 0x4000
	v_add3_u32 v84, v146, v84, s6
	v_lshl_add_u32 v85, v85, 2, v137
	ds_write_b32 v85, v84 offset:3072
.LBB0_890:
	s_or_b64 exec, exec, s[10:11]
	v_cmp_gt_u32_e64 s[74:75], v80, v142
	s_mov_b64 s[72:73], vcc
	v_max_f32_e32 v84, 0, v89
	v_max_f32_e32 v85, 0, v93
	v_pk_mul_f32 v[84:85], v[84:85], v[110:111]
	v_max_f32_e32 v80, 0, v97
	v_max_f32_e32 v81, 0, v81
	v_pk_mul_f32 v[80:81], v[80:81], v[112:113]
	v_add_f32_e32 v84, v84, v85
	v_add_f32_e32 v80, v84, v80
	v_add_f32_e32 v80, v80, v81
	v_add_f32_e32 v80, 0, v80
	v_ashrrev_i32_e32 v84, 31, v80
	v_or_b32_e32 v84, 0x80000000, v84
	v_xor_b32_e32 v81, v84, v80
	v_and_b32_e32 v80, s30, v81
	v_cmp_eq_u32_e64 s[8:9], v80, v143
	v_cmp_eq_u32_e32 vcc, s3, v81
	v_cmp_ne_u32_e64 s[6:7], s3, v81
	s_and_saveexec_b64 s[10:11], s[8:9]
	s_cbranch_execz .LBB0_894
	v_and_b32_e32 v84, s31, v81
	v_lshlrev_b32_e32 v85, 1, v84
	v_and_b32_e32 v85, -4, v85
	v_lshlrev_b32_e32 v84, 4, v84
	v_add_u32_e32 v85, v137, v85
	v_lshlrev_b32_e64 v84, v84, 1
	ds_add_u32 v85, v84 offset:4112
	s_and_b64 exec, exec, s[6:7]
	s_cbranch_execz .LBB0_894
	ds_add_rtn_u32 v84, v137, v174 offset:7440
	s_waitcnt lgkmcnt(0)
	v_cmp_gt_u32_e64 s[6:7], 64, v84
	s_and_b64 exec, exec, s[6:7]
	v_and_b32_e32 v81, 0x3ff, v81
	s_movk_i32 s6, 0x4000
	v_add3_u32 v81, v146, v81, s6
	v_lshl_add_u32 v84, v84, 2, v137
	ds_write_b32 v84, v81 offset:7184
.LBB0_894:
	s_or_b64 exec, exec, s[10:11]
	v_cmp_gt_u32_e64 s[78:79], v80, v143
	s_mov_b64 s[76:77], vcc
	v_max_f32_e32 v80, 0, v90
	v_max_f32_e32 v81, 0, v94
	v_pk_mul_f32 v[80:81], v[80:81], v[114:115]
	v_max_f32_e32 v84, 0, v98
	v_max_f32_e32 v85, 0, v82
	v_pk_mul_f32 v[84:85], v[84:85], v[116:117]
	v_add_f32_e32 v80, v80, v81
	v_add_f32_e32 v80, v80, v84
	v_add_f32_e32 v80, v80, v85
	v_add_f32_e32 v80, 0, v80
	v_ashrrev_i32_e32 v82, 31, v80
	v_or_b32_e32 v82, 0x80000000, v82
	v_xor_b32_e32 v81, v82, v80
	v_and_b32_e32 v80, s30, v81
	v_cmp_eq_u32_e64 s[8:9], v80, v144
	v_cmp_eq_u32_e32 vcc, s3, v81
	v_cmp_ne_u32_e64 s[6:7], s3, v81
	s_and_saveexec_b64 s[10:11], s[8:9]
	s_cbranch_execz .LBB0_898
	v_and_b32_e32 v82, s31, v81
	v_lshlrev_b32_e32 v84, 1, v82
	v_and_b32_e32 v84, -4, v84
	v_lshlrev_b32_e32 v82, 4, v82
	v_add_u32_e32 v84, v137, v84
	v_lshlrev_b32_e64 v82, v82, 1
	ds_add_u32 v84, v82 offset:8224
	s_and_b64 exec, exec, s[6:7]
	s_cbranch_execz .LBB0_898
	ds_add_rtn_u32 v82, v137, v174 offset:11552
	s_waitcnt lgkmcnt(0)
	v_cmp_gt_u32_e64 s[6:7], 64, v82
	s_and_b64 exec, exec, s[6:7]
	v_and_b32_e32 v81, 0x3ff, v81
	s_movk_i32 s6, 0x4000
	v_add3_u32 v81, v146, v81, s6
	v_lshl_add_u32 v82, v82, 2, v137
	ds_write_b32 v82, v81 offset:11296
; #define MFMA16(a, b, c) __builtin_amdgcn_mfma_f32_16x16x32_f16((a), (b), (c), 0, 0, 0)
; template <int MODE> ...
;     ...
;     for (int kt = 0; kt < 4; ++kt) {
;       f32x4 sh[4];
; #pragma unroll
;       for (int h = 0; h < 4; ++h) {
;         sh[h] = (f32x4){0.f, 0.f, 0.f, 0.f};
; #pragma unroll
;         for (int ks = 0; ks < 2; ++ks) sh[h] = MFMA16(qf[h][ks], kf[kt][ks], sh[h]);
;       }
; #pragma unroll
;       for (int j = 0; j < 4; ++j) {
;         float sc = w[j][0] * fmaxf(sh[0][j], 0.f) + w[j][1] * fmaxf(sh[1][j], 0.f) + w[j][2] * fmaxf(sh[2][j], 0.f) + w[j][3] * fmaxf(sh[3][j], 0.f);
;         sc += 0.0f;
;         const unsigned u = sortable(sc);
;         if (MODE == 4) {
;           const unsigned um = u & himask;
;           const bool eq = um == pfx[j], zr = u == 0x80000000u;
;           unsigned* qx = hist + (4 * g + j) * C1_HP + 512;
;           if (eq) {
;             const unsigned bin = u & bmask; atomicAdd(&hist[(4 * g + j) * C1_HP + (bin >> 1)], 1u << ((bin & 1u) * 16u));
;             if (!zr) { const unsigned idx = atomicAdd(&qx[320], 1u); if (idx < 64u) qx[256 + idx] = ((unsigned)n << 16) | ((unsigned)(kt * 16 + lr) << 10) | (u & 1023u); }
;           }
;           word[j] |= (u64)((unsigned)(__ballot(um > pfx[j]) >> (16 * g)) & 0xffffu) << (16 * kt);
;           zword[j] |= (u64)((unsigned)(__ballot(zr) >> (16 * g)) & 0xffffu) << (16 * kt);
;         } else if (MODE == 0 || MODE == 3) {
;           if (MODE == 3) base[j] += __popc((unsigned)(__ballot(u == 0x80000000u) >> (16 * g)) & 0xffffu);
;           if (((u ^ pfx[j]) & himask) == 0u) { const unsigned bin = (u >> shift) & bmask; atomicAdd(&hist[(4 * g + j) * C1_HP + (bin >> 1)], 1u << ((bin & 1u) * 16u)); }
;         } else {
;           const bool eq = u == pfx[j];
;           const unsigned fe = (unsigned)(__ballot(eq) >> (16 * g)) & 0xffffu;
;           if (MODE == 1) {
;             base[j] += __popc(fe);
;           } else {
;             const unsigned rank = base[j] + __popc(fe & ((1u << lr) - 1u));
;             const bool sel = (u > pfx[j]) || (eq && rank < need[j]);
;             base[j] += __popc(fe);
;             const unsigned fs = (unsigned)(__ballot(sel) >> (16 * g)) & 0xffffu;
;             word[j] |= (u64)fs << (16 * kt);
;           }
;         }
;       }
.LBB0_898:
	s_or_b64 exec, exec, s[10:11]
	v_cmp_gt_u32_e64 s[86:87], v80, v144
	s_mov_b64 s[84:85], vcc
	v_max_f32_e32 v80, 0, v91
	v_max_f32_e32 v81, 0, v95
	v_pk_mul_f32 v[80:81], v[80:81], v[118:119]
	v_max_f32_e32 v82, 0, v99
	v_max_f32_e32 v83, 0, v83
	v_pk_mul_f32 v[82:83], v[82:83], v[120:121]
	v_add_f32_e32 v80, v80, v81
	v_add_f32_e32 v80, v80, v82
	v_add_f32_e32 v80, v80, v83
	v_add_f32_e32 v80, 0, v80
	v_ashrrev_i32_e32 v82, 31, v80
	v_or_b32_e32 v82, 0x80000000, v82
	v_xor_b32_e32 v81, v82, v80
	v_and_b32_e32 v80, s30, v81
	v_cmp_eq_u32_e64 s[8:9], v80, v145
	v_cmp_eq_u32_e32 vcc, s3, v81
	v_cmp_ne_u32_e64 s[6:7], s3, v81
	s_and_saveexec_b64 s[10:11], s[8:9]
	s_cbranch_execz .LBB0_902
	v_and_b32_e32 v82, s31, v81
	v_lshlrev_b32_e32 v83, 1, v82
	v_and_b32_e32 v83, -4, v83
	v_lshlrev_b32_e32 v82, 4, v82
	v_add_u32_e32 v83, v137, v83
	v_lshlrev_b32_e64 v82, v82, 1
	ds_add_u32 v83, v82 offset:12336
	s_and_b64 exec, exec, s[6:7]
	s_cbranch_execz .LBB0_902
	ds_add_rtn_u32 v82, v137, v174 offset:15664
	s_waitcnt lgkmcnt(0)
	v_cmp_gt_u32_e64 s[6:7], 64, v82
	s_and_b64 exec, exec, s[6:7]
	v_and_b32_e32 v81, 0x3ff, v81
	s_movk_i32 s6, 0x4000
	v_add3_u32 v81, v146, v81, s6
	v_lshl_add_u32 v82, v82, 2, v137
	ds_write_b32 v82, v81 offset:15408
.LBB0_902:
	s_or_b64 exec, exec, s[10:11]
	v_cmp_gt_u32_e64 s[82:83], v80, v145
	s_mov_b64 s[80:81], vcc
	s_waitcnt vmcnt(11)
	v_mfma_f32_16x16x32_f16 v[80:83], v[24:27], v[72:75], 0
	v_mfma_f32_16x16x32_f16 v[84:87], v[4:7], v[72:75], 0
	v_mfma_f32_16x16x32_f16 v[88:91], v[12:15], v[72:75], 0
	v_mfma_f32_16x16x32_f16 v[72:75], v[20:23], v[72:75], 0
	s_waitcnt vmcnt(10)
	v_mfma_f32_16x16x32_f16 v[80:83], v[0:3], v[76:79], v[80:83]
	v_mfma_f32_16x16x32_f16 v[84:87], v[8:11], v[76:79], v[84:87]
	v_mfma_f32_16x16x32_f16 v[88:91], v[16:19], v[76:79], v[88:91]
	v_mfma_f32_16x16x32_f16 v[72:75], v[28:31], v[76:79], v[72:75]
	s_nop 4
	v_max_f32_e32 v76, 0, v80
	v_max_f32_e32 v77, 0, v84
	v_pk_mul_f32 v[76:77], v[76:77], v[106:107]
	v_max_f32_e32 v78, 0, v88
	v_max_f32_e32 v79, 0, v72
	v_pk_mul_f32 v[78:79], v[78:79], v[108:109]
	v_add_f32_e32 v72, v76, v77
	v_add_f32_e32 v72, v72, v78
	v_add_f32_e32 v72, v72, v79
	v_add_f32_e32 v72, 0, v72
	v_ashrrev_i32_e32 v77, 31, v72
	v_or_b32_e32 v77, 0x80000000, v77
	v_xor_b32_e32 v76, v77, v72
	v_and_b32_e32 v72, s30, v76
	v_cmp_eq_u32_e64 s[8:9], v72, v142
	v_cmp_eq_u32_e32 vcc, s3, v76
	v_cmp_ne_u32_e64 s[6:7], s3, v76
	s_and_saveexec_b64 s[10:11], s[8:9]
	s_cbranch_execz .LBB0_906
	v_and_b32_e32 v77, s31, v76
	v_lshlrev_b32_e32 v78, 1, v77
	v_and_b32_e32 v78, -4, v78
	v_lshlrev_b32_e32 v77, 4, v77
	v_add_u32_e32 v78, v137, v78
	v_lshlrev_b32_e64 v77, v77, 1
	ds_add_u32 v78, v77
	s_and_b64 exec, exec, s[6:7]
	s_cbranch_execz .LBB0_906
	ds_add_rtn_u32 v77, v137, v174 offset:3328
	s_waitcnt lgkmcnt(0)
	v_cmp_gt_u32_e64 s[6:7], 64, v77
	s_and_b64 exec, exec, s[6:7]
	v_and_b32_e32 v76, 0x3ff, v76
	s_mov_b32 s6, 0x8000
	v_add3_u32 v76, v146, v76, s6
	v_lshl_add_u32 v77, v77, 2, v137
	ds_write_b32 v77, v76 offset:3072
.LBB0_906:
	s_or_b64 exec, exec, s[10:11]
	v_cmp_gt_u32_e64 s[88:89], v72, v142
	s_mov_b64 s[90:91], vcc
	v_max_f32_e32 v76, 0, v81
	v_max_f32_e32 v77, 0, v85
	v_pk_mul_f32 v[76:77], v[76:77], v[110:111]
	v_max_f32_e32 v72, 0, v89
	v_max_f32_e32 v73, 0, v73
	v_pk_mul_f32 v[72:73], v[72:73], v[112:113]
	v_add_f32_e32 v76, v76, v77
	v_add_f32_e32 v72, v76, v72
	v_add_f32_e32 v72, v72, v73
	v_add_f32_e32 v72, 0, v72
	v_ashrrev_i32_e32 v76, 31, v72
	v_or_b32_e32 v76, 0x80000000, v76
	v_xor_b32_e32 v73, v76, v72
	v_and_b32_e32 v72, s30, v73
	v_cmp_eq_u32_e64 s[8:9], v72, v143
	v_cmp_eq_u32_e32 vcc, s3, v73
	v_cmp_ne_u32_e64 s[6:7], s3, v73
	s_and_saveexec_b64 s[10:11], s[8:9]
	s_cbranch_execz .LBB0_910
	v_and_b32_e32 v76, s31, v73
	v_lshlrev_b32_e32 v77, 1, v76
	v_and_b32_e32 v77, -4, v77
	v_lshlrev_b32_e32 v76, 4, v76
	v_add_u32_e32 v77, v137, v77
	v_lshlrev_b32_e64 v76, v76, 1
	ds_add_u32 v77, v76 offset:4112
	s_and_b64 exec, exec, s[6:7]
	s_cbranch_execz .LBB0_910
	ds_add_rtn_u32 v76, v137, v174 offset:7440
	s_waitcnt lgkmcnt(0)
	v_cmp_gt_u32_e64 s[6:7], 64, v76
	s_and_b64 exec, exec, s[6:7]
	v_and_b32_e32 v73, 0x3ff, v73
	s_mov_b32 s6, 0x8000
	v_add3_u32 v73, v146, v73, s6
	v_lshl_add_u32 v76, v76, 2, v137
	ds_write_b32 v76, v73 offset:7184
.LBB0_910:
	s_or_b64 exec, exec, s[10:11]
	v_cmp_gt_u32_e64 s[92:93], v72, v143
	s_mov_b64 s[94:95], vcc
	v_max_f32_e32 v72, 0, v82
	v_max_f32_e32 v73, 0, v86
	v_pk_mul_f32 v[72:73], v[72:73], v[114:115]
	v_max_f32_e32 v76, 0, v90
	v_max_f32_e32 v77, 0, v74
	v_pk_mul_f32 v[76:77], v[76:77], v[116:117]
	v_add_f32_e32 v72, v72, v73
	v_add_f32_e32 v72, v72, v76
	v_add_f32_e32 v72, v72, v77
	v_add_f32_e32 v72, 0, v72
	v_ashrrev_i32_e32 v74, 31, v72
	v_or_b32_e32 v74, 0x80000000, v74
	v_xor_b32_e32 v73, v74, v72
	v_and_b32_e32 v72, s30, v73
	v_cmp_eq_u32_e64 s[8:9], v72, v144
	v_cmp_eq_u32_e32 vcc, s3, v73
	v_cmp_ne_u32_e64 s[6:7], s3, v73
	s_and_saveexec_b64 s[10:11], s[8:9]
	s_cbranch_execz .LBB0_914
	v_and_b32_e32 v74, s31, v73
	v_lshlrev_b32_e32 v76, 1, v74
	v_and_b32_e32 v76, -4, v76
	v_lshlrev_b32_e32 v74, 4, v74
	v_add_u32_e32 v76, v137, v76
	v_lshlrev_b32_e64 v74, v74, 1
	ds_add_u32 v76, v74 offset:8224
	s_and_b64 exec, exec, s[6:7]
	s_cbranch_execz .LBB0_914
	ds_add_rtn_u32 v74, v137, v174 offset:11552
	s_waitcnt lgkmcnt(0)
	v_cmp_gt_u32_e64 s[6:7], 64, v74
	s_and_b64 exec, exec, s[6:7]
	v_and_b32_e32 v73, 0x3ff, v73
	s_mov_b32 s6, 0x8000
	v_add3_u32 v73, v146, v73, s6
	v_lshl_add_u32 v74, v74, 2, v137
	ds_write_b32 v74, v73 offset:11296
; #define MFMA16(a, b, c) __builtin_amdgcn_mfma_f32_16x16x32_f16((a), (b), (c), 0, 0, 0)
; template <int MODE> ...
;     ...
;     for (int kt = 0; kt < 4; ++kt) {
;       f32x4 sh[4];
; #pragma unroll
;       for (int h = 0; h < 4; ++h) {
;         sh[h] = (f32x4){0.f, 0.f, 0.f, 0.f};
; #pragma unroll
;         for (int ks = 0; ks < 2; ++ks) sh[h] = MFMA16(qf[h][ks], kf[kt][ks], sh[h]);
;       }
; #pragma unroll
;       for (int j = 0; j < 4; ++j) {
;         float sc = w[j][0] * fmaxf(sh[0][j], 0.f) + w[j][1] * fmaxf(sh[1][j], 0.f) + w[j][2] * fmaxf(sh[2][j], 0.f) + w[j][3] * fmaxf(sh[3][j], 0.f);
;         sc += 0.0f;
;         const unsigned u = sortable(sc);
;         if (MODE == 4) {
;           const unsigned um = u & himask;
;           const bool eq = um == pfx[j], zr = u == 0x80000000u;
;           unsigned* qx = hist + (4 * g + j) * C1_HP + 512;
;           if (eq) {
;             const unsigned bin = u & bmask; atomicAdd(&hist[(4 * g + j) * C1_HP + (bin >> 1)], 1u << ((bin & 1u) * 16u));
;             if (!zr) { const unsigned idx = atomicAdd(&qx[320], 1u); if (idx < 64u) qx[256 + idx] = ((unsigned)n << 16) | ((unsigned)(kt * 16 + lr) << 10) | (u & 1023u); }
;           }
;           word[j] |= (u64)((unsigned)(__ballot(um > pfx[j]) >> (16 * g)) & 0xffffu) << (16 * kt);
;           zword[j] |= (u64)((unsigned)(__ballot(zr) >> (16 * g)) & 0xffffu) << (16 * kt);
;         } else if (MODE == 0 || MODE == 3) {
;           if (MODE == 3) base[j] += __popc((unsigned)(__ballot(u == 0x80000000u) >> (16 * g)) & 0xffffu);
;           if (((u ^ pfx[j]) & himask) == 0u) { const unsigned bin = (u >> shift) & bmask; atomicAdd(&hist[(4 * g + j) * C1_HP + (bin >> 1)], 1u << ((bin & 1u) * 16u)); }
;         } else {
;           const bool eq = u == pfx[j];
;           const unsigned fe = (unsigned)(__ballot(eq) >> (16 * g)) & 0xffffu;
;           if (MODE == 1) {
;             base[j] += __popc(fe);
;           } else {
;             const unsigned rank = base[j] + __popc(fe & ((1u << lr) - 1u));
;             const bool sel = (u > pfx[j]) || (eq && rank < need[j]);
;             base[j] += __popc(fe);
;             const unsigned fs = (unsigned)(__ballot(sel) >> (16 * g)) & 0xffffu;
;             word[j] |= (u64)fs << (16 * kt);
;           }
;         }
;       }
.LBB0_914:
	s_or_b64 exec, exec, s[10:11]
	v_cmp_gt_u32_e64 s[10:11], v72, v144
	s_mov_b64 s[8:9], vcc
	v_max_f32_e32 v72, 0, v83
	v_max_f32_e32 v73, 0, v87
	v_pk_mul_f32 v[72:73], v[72:73], v[118:119]
	v_max_f32_e32 v74, 0, v91
	v_max_f32_e32 v75, 0, v75
	v_pk_mul_f32 v[74:75], v[74:75], v[120:121]
	v_add_f32_e32 v72, v72, v73
	v_add_f32_e32 v72, v72, v74
	v_add_f32_e32 v72, v72, v75
	v_add_f32_e32 v72, 0, v72
	v_ashrrev_i32_e32 v74, 31, v72
	v_or_b32_e32 v74, 0x80000000, v74
	v_xor_b32_e32 v73, v74, v72
	v_and_b32_e32 v72, s30, v73
	v_cmp_eq_u32_e64 s[12:13], v72, v145
	v_cmp_eq_u32_e32 vcc, s3, v73
	v_cmp_ne_u32_e64 s[6:7], s3, v73
	s_and_saveexec_b64 s[14:15], s[12:13]
	s_cbranch_execz .LBB0_918
	v_and_b32_e32 v74, s31, v73
	v_lshlrev_b32_e32 v75, 1, v74
	v_and_b32_e32 v75, -4, v75
	v_lshlrev_b32_e32 v74, 4, v74
	v_add_u32_e32 v75, v137, v75
	v_lshlrev_b32_e64 v74, v74, 1
	ds_add_u32 v75, v74 offset:12336
	s_and_b64 exec, exec, s[6:7]
	s_cbranch_execz .LBB0_918
	ds_add_rtn_u32 v74, v137, v174 offset:15664
	s_waitcnt lgkmcnt(0)
	v_cmp_gt_u32_e64 s[6:7], 64, v74
	s_and_b64 exec, exec, s[6:7]
	v_and_b32_e32 v73, 0x3ff, v73
	s_mov_b32 s6, 0x8000
	v_add3_u32 v73, v146, v73, s6
	v_lshl_add_u32 v74, v74, 2, v137
	ds_write_b32 v74, v73 offset:15408
.LBB0_918:
	s_or_b64 exec, exec, s[14:15]
	v_cmp_gt_u32_e64 s[96:97], v72, v145
	s_mov_b64 s[6:7], vcc
	s_waitcnt vmcnt(9)
	v_mfma_f32_16x16x32_f16 v[72:75], v[24:27], v[64:67], 0
	v_mfma_f32_16x16x32_f16 v[76:79], v[4:7], v[64:67], 0
	v_mfma_f32_16x16x32_f16 v[80:83], v[12:15], v[64:67], 0
	v_mfma_f32_16x16x32_f16 v[64:67], v[20:23], v[64:67], 0
	s_waitcnt vmcnt(8)
	v_mfma_f32_16x16x32_f16 v[72:75], v[0:3], v[68:71], v[72:75]
	v_mfma_f32_16x16x32_f16 v[76:79], v[8:11], v[68:71], v[76:79]
	v_mfma_f32_16x16x32_f16 v[80:83], v[16:19], v[68:71], v[80:83]
	v_mfma_f32_16x16x32_f16 v[64:67], v[28:31], v[68:71], v[64:67]
	s_nop 4
	v_max_f32_e32 v68, 0, v72
	v_max_f32_e32 v69, 0, v76
	v_pk_mul_f32 v[68:69], v[68:69], v[106:107]
	v_max_f32_e32 v70, 0, v80
	v_max_f32_e32 v71, 0, v64
	v_pk_mul_f32 v[70:71], v[70:71], v[108:109]
	v_add_f32_e32 v64, v68, v69
	v_add_f32_e32 v64, v64, v70
	v_add_f32_e32 v64, v64, v71
	v_add_f32_e32 v64, 0, v64
	v_ashrrev_i32_e32 v69, 31, v64
	v_or_b32_e32 v69, 0x80000000, v69
	v_xor_b32_e32 v68, v69, v64
	v_and_b32_e32 v64, s30, v68
	v_cmp_eq_u32_e64 s[14:15], v64, v142
	v_cmp_eq_u32_e32 vcc, s3, v68
	v_cmp_ne_u32_e64 s[12:13], s3, v68
	s_and_saveexec_b64 s[16:17], s[14:15]
	s_cbranch_execz .LBB0_922
	v_and_b32_e32 v69, s31, v68
	v_lshlrev_b32_e32 v70, 1, v69
	v_and_b32_e32 v70, -4, v70
	v_lshlrev_b32_e32 v69, 4, v69
	v_add_u32_e32 v70, v137, v70
	v_lshlrev_b32_e64 v69, v69, 1
	ds_add_u32 v70, v69
	s_and_b64 exec, exec, s[12:13]
	s_cbranch_execz .LBB0_922
	ds_add_rtn_u32 v69, v137, v174 offset:3328
	s_waitcnt lgkmcnt(0)
	v_cmp_gt_u32_e64 s[12:13], 64, v69
	s_and_b64 exec, exec, s[12:13]
	v_and_b32_e32 v68, 0x3ff, v68
	s_mov_b32 s12, 0xc000
	v_add3_u32 v68, v146, v68, s12
	v_lshl_add_u32 v69, v69, 2, v137
	ds_write_b32 v69, v68 offset:3072
.LBB0_922:
	s_or_b64 exec, exec, s[16:17]
	v_cmp_gt_u32_e64 s[14:15], v64, v142
	s_mov_b64 s[12:13], vcc
	v_max_f32_e32 v68, 0, v73
	v_max_f32_e32 v69, 0, v77
	v_pk_mul_f32 v[68:69], v[68:69], v[110:111]
	v_max_f32_e32 v64, 0, v81
	v_max_f32_e32 v65, 0, v65
	v_pk_mul_f32 v[64:65], v[64:65], v[112:113]
	v_add_f32_e32 v68, v68, v69
	v_add_f32_e32 v64, v68, v64
	v_add_f32_e32 v64, v64, v65
	v_add_f32_e32 v64, 0, v64
	v_ashrrev_i32_e32 v68, 31, v64
	v_or_b32_e32 v68, 0x80000000, v68
	v_xor_b32_e32 v65, v68, v64
	v_and_b32_e32 v64, s30, v65
	v_cmp_eq_u32_e64 s[18:19], v64, v143
	v_cmp_eq_u32_e32 vcc, s3, v65
	v_cmp_ne_u32_e64 s[16:17], s3, v65
	s_and_saveexec_b64 s[20:21], s[18:19]
	s_cbranch_execz .LBB0_926
	v_and_b32_e32 v68, s31, v65
	v_lshlrev_b32_e32 v69, 1, v68
	v_and_b32_e32 v69, -4, v69
	v_lshlrev_b32_e32 v68, 4, v68
	v_add_u32_e32 v69, v137, v69
	v_lshlrev_b32_e64 v68, v68, 1
	ds_add_u32 v69, v68 offset:4112
	s_and_b64 exec, exec, s[16:17]
	s_cbranch_execz .LBB0_926
	ds_add_rtn_u32 v68, v137, v174 offset:7440
	s_waitcnt lgkmcnt(0)
	v_cmp_gt_u32_e64 s[16:17], 64, v68
	s_and_b64 exec, exec, s[16:17]
	v_and_b32_e32 v65, 0x3ff, v65
	s_mov_b32 s16, 0xc000
	v_add3_u32 v65, v146, v65, s16
	v_lshl_add_u32 v68, v68, 2, v137
	ds_write_b32 v68, v65 offset:7184
.LBB0_926:
	s_or_b64 exec, exec, s[20:21]
	v_cmp_gt_u32_e64 s[18:19], v64, v143
	s_mov_b64 s[16:17], vcc
	v_max_f32_e32 v64, 0, v74
	v_max_f32_e32 v65, 0, v78
	v_pk_mul_f32 v[64:65], v[64:65], v[114:115]
	v_max_f32_e32 v68, 0, v82
	v_max_f32_e32 v69, 0, v66
	v_pk_mul_f32 v[68:69], v[68:69], v[116:117]
	v_add_f32_e32 v64, v64, v65
	v_add_f32_e32 v64, v64, v68
	v_add_f32_e32 v64, v64, v69
	v_add_f32_e32 v64, 0, v64
	v_ashrrev_i32_e32 v66, 31, v64
	v_or_b32_e32 v66, 0x80000000, v66
	v_xor_b32_e32 v65, v66, v64
	v_and_b32_e32 v64, s30, v65
	v_cmp_eq_u32_e64 s[22:23], v64, v144
	v_cmp_eq_u32_e64 s[20:21], s3, v65
	v_cmp_ne_u32_e32 vcc, s3, v65
	s_and_saveexec_b64 s[24:25], s[22:23]
	s_cbranch_execz .LBB0_930
	v_and_b32_e32 v66, s31, v65
	v_lshlrev_b32_e32 v68, 1, v66
	v_and_b32_e32 v68, -4, v68
	v_lshlrev_b32_e32 v66, 4, v66
	v_add_u32_e32 v68, v137, v68
	v_lshlrev_b32_e64 v66, v66, 1
	ds_add_u32 v68, v66 offset:8224
	s_and_b64 exec, exec, vcc
	s_cbranch_execz .LBB0_930
	ds_add_rtn_u32 v66, v137, v174 offset:11552
	s_waitcnt lgkmcnt(0)
	v_cmp_gt_u32_e32 vcc, 64, v66
	s_and_b64 exec, exec, vcc
	v_and_b32_e32 v65, 0x3ff, v65
	s_mov_b32 s22, 0xc000
	v_add3_u32 v65, v146, v65, s22
	v_lshl_add_u32 v66, v66, 2, v137
	ds_write_b32 v66, v65 offset:11296
